# v22: v21 + no per-call acquire for kind 5 (its A panel MIX(pm), residual rows and weights cannot be stale in this CU's L1: first-touch addresses or loaded after kind 3's acquire)
# speedup vs baseline: 1.0059x; 1.0053x over previous
.LBB0_691:
	s_or_b64 exec, exec, s[2:3]
	s_andn2_b64 vcc, exec, s[70:71]
	s_cbranch_vccnz .LBB0_693
	s_cmp_eq_u32 s42, 2
	s_cbranch_scc1 .LBB0_693
	s_cmp_eq_u32 s42, 5
	s_cbranch_scc1 .LBB0_693
	s_waitcnt vmcnt(0)
	buffer_inv sc1
	s_waitcnt vmcnt(0)
